# nsacmp item: 64 position-bias LUT lookups prefetched branch-free up front (address slices replayed), masked blocks take the value
# baseline (speedup 1.0000x reference)
; DI void nsacmp_item(const Params& p, int L, int item, char* smem) {
;     ...
;   const int ncv = spos >= 31 ? (spos - 31) / 16 + 1 : 0;
;   const float* lutl = lut + h * 132;
;   float mx = -INFINITY;
; #pragma unroll
;   for (int ct = 0; ct < 4; ++ct)
; #pragma unroll
;     for (int i = 0; i < 16; ++i) {
;       const int c = 32 * ct + (i & 3) + 8 * (i >> 2) + 4 * hh;
;       int dd = spos - 16 * c - 31; dd = dd < 0 ? 0 : (dd > 128 ? 128 : dd);
;       const float sv = (c < ncv) ? (sc[ct][i] + lutl[dd]) : -INFINITY;
;       sc[ct][i] = sv; mx = fmaxf(mx, sv);
;     }
.LBB0_234:
	v_subrev_u32_e32 v64, 31, v81
	v_lshrrev_b32_e32 v67, 4, v64
	v_lshlrev_b32_e32 v64, 2, v94
	v_cmp_lt_u32_e32 vcc, 30, v81
	v_cmp_ge_u32_e64 s[2:3], v67, v64
	v_lshlrev_b32_e32 v66, 6, v94
	s_mul_i32 s5, s4, 0x210
	s_and_b64 s[16:17], vcc, s[2:3]
	v_mov_b32_e32 v65, 0xff800000
	v_sub_u32_e32 v68, v81, v66
	v_mov_b32_e32 v66, 0xff800000
	v_med3_i32 v110, v68, 31, v236
	v_lshl_add_u32 v110, v110, 2, s5
	ds_read_b32 v110, v110 offset:35716
	v_add_u32_e32 v111, -16, v68
	v_med3_i32 v111, v111, 31, v236
	v_lshl_add_u32 v111, v111, 2, s5
	ds_read_b32 v111, v111 offset:35716
	v_or_b32_e32 v112, 2, v64
	v_lshlrev_b32_e32 v112, 4, v112
	v_sub_u32_e32 v112, v81, v112
	v_med3_i32 v112, v112, 31, v236
	v_lshl_add_u32 v112, v112, 2, s5
	ds_read_b32 v112, v112 offset:35716
	v_or_b32_e32 v113, 3, v64
	v_lshlrev_b32_e32 v113, 4, v113
	v_sub_u32_e32 v113, v81, v113
	v_med3_i32 v113, v113, 31, v236
	v_lshl_add_u32 v113, v113, 2, s5
	ds_read_b32 v113, v113 offset:35716
	v_or_b32_e32 v114, 8, v64
	v_lshlrev_b32_e32 v114, 4, v114
	v_sub_u32_e32 v114, v81, v114
	v_med3_i32 v114, v114, 31, v236
	v_lshl_add_u32 v114, v114, 2, s5
	ds_read_b32 v114, v114 offset:35716
	v_or_b32_e32 v115, 9, v64
	v_lshlrev_b32_e32 v115, 4, v115
	v_sub_u32_e32 v115, v81, v115
	v_med3_i32 v115, v115, 31, v236
	v_lshl_add_u32 v115, v115, 2, s5
	ds_read_b32 v115, v115 offset:35716
	v_or_b32_e32 v116, 10, v64
	v_lshlrev_b32_e32 v116, 4, v116
	v_sub_u32_e32 v116, v81, v116
	v_med3_i32 v116, v116, 31, v236
	v_lshl_add_u32 v116, v116, 2, s5
	ds_read_b32 v116, v116 offset:35716
	v_or_b32_e32 v117, 11, v64
	v_lshlrev_b32_e32 v117, 4, v117
	v_sub_u32_e32 v117, v81, v117
	v_med3_i32 v117, v117, 31, v236
	v_lshl_add_u32 v117, v117, 2, s5
	ds_read_b32 v117, v117 offset:35716
	s_waitcnt lgkmcnt(4)
	v_or_b32_e32 v118, 16, v64
	v_lshlrev_b32_e32 v118, 4, v118
	v_sub_u32_e32 v118, v81, v118
	v_med3_i32 v118, v118, 31, v236
	v_lshl_add_u32 v118, v118, 2, s5
	ds_read_b32 v118, v118 offset:35716
	v_or_b32_e32 v119, 17, v64
	v_lshlrev_b32_e32 v119, 4, v119
	v_sub_u32_e32 v119, v81, v119
	v_med3_i32 v119, v119, 31, v236
	v_lshl_add_u32 v119, v119, 2, s5
	ds_read_b32 v119, v119 offset:35716
	v_or_b32_e32 v120, 18, v64
	v_lshlrev_b32_e32 v120, 4, v120
	v_sub_u32_e32 v120, v81, v120
	v_med3_i32 v120, v120, 31, v236
	v_lshl_add_u32 v120, v120, 2, s5
	ds_read_b32 v120, v120 offset:35716
	v_or_b32_e32 v121, 19, v64
	v_lshlrev_b32_e32 v121, 4, v121
	v_sub_u32_e32 v121, v81, v121
	v_med3_i32 v121, v121, 31, v236
	v_lshl_add_u32 v121, v121, 2, s5
	ds_read_b32 v121, v121 offset:35716
	v_or_b32_e32 v122, 24, v64
	v_lshlrev_b32_e32 v122, 4, v122
	v_sub_u32_e32 v122, v81, v122
	v_med3_i32 v122, v122, 31, v236
	v_lshl_add_u32 v122, v122, 2, s5
	ds_read_b32 v122, v122 offset:35716
	v_or_b32_e32 v123, 25, v64
	v_lshlrev_b32_e32 v123, 4, v123
	v_sub_u32_e32 v123, v81, v123
	v_med3_i32 v123, v123, 31, v236
	v_lshl_add_u32 v123, v123, 2, s5
	ds_read_b32 v123, v123 offset:35716
	v_or_b32_e32 v124, 26, v64
	v_lshlrev_b32_e32 v124, 4, v124
	v_sub_u32_e32 v124, v81, v124
	v_med3_i32 v124, v124, 31, v236
	v_lshl_add_u32 v124, v124, 2, s5
	ds_read_b32 v124, v124 offset:35716
	v_or_b32_e32 v125, 27, v64
	v_lshlrev_b32_e32 v125, 4, v125
	v_sub_u32_e32 v125, v81, v125
	v_med3_i32 v125, v125, 31, v236
	v_lshl_add_u32 v125, v125, 2, s5
	ds_read_b32 v125, v125 offset:35716
	s_waitcnt lgkmcnt(4)
	v_or_b32_e32 v126, 32, v64
	v_lshlrev_b32_e32 v126, 4, v126
	v_sub_u32_e32 v126, v81, v126
	v_med3_i32 v126, v126, 31, v236
	v_lshl_add_u32 v126, v126, 2, s5
	ds_read_b32 v126, v126 offset:35716
	v_or_b32_e32 v127, 33, v64
	v_lshlrev_b32_e32 v127, 4, v127
	v_sub_u32_e32 v127, v81, v127
	v_med3_i32 v127, v127, 31, v236
	v_lshl_add_u32 v127, v127, 2, s5
	ds_read_b32 v127, v127 offset:35716
	v_or_b32_e32 v128, 34, v64
	v_lshlrev_b32_e32 v128, 4, v128
	v_sub_u32_e32 v128, v81, v128
	v_med3_i32 v128, v128, 31, v236
	v_lshl_add_u32 v128, v128, 2, s5
	ds_read_b32 v128, v128 offset:35716
	v_or_b32_e32 v129, 35, v64
	v_lshlrev_b32_e32 v129, 4, v129
	v_sub_u32_e32 v129, v81, v129
	v_med3_i32 v129, v129, 31, v236
	v_lshl_add_u32 v129, v129, 2, s5
	ds_read_b32 v129, v129 offset:35716
	v_or_b32_e32 v130, 40, v64
	v_lshlrev_b32_e32 v130, 4, v130
	v_sub_u32_e32 v130, v81, v130
	v_med3_i32 v130, v130, 31, v236
	v_lshl_add_u32 v130, v130, 2, s5
	ds_read_b32 v130, v130 offset:35716
	v_or_b32_e32 v131, 41, v64
	v_lshlrev_b32_e32 v131, 4, v131
	v_sub_u32_e32 v131, v81, v131
	v_med3_i32 v131, v131, 31, v236
	v_lshl_add_u32 v131, v131, 2, s5
	ds_read_b32 v131, v131 offset:35716
	v_or_b32_e32 v132, 42, v64
	v_lshlrev_b32_e32 v132, 4, v132
	v_sub_u32_e32 v132, v81, v132
	v_med3_i32 v132, v132, 31, v236
	v_lshl_add_u32 v132, v132, 2, s5
	ds_read_b32 v132, v132 offset:35716
	v_or_b32_e32 v133, 43, v64
	v_lshlrev_b32_e32 v133, 4, v133
	v_sub_u32_e32 v133, v81, v133
	v_med3_i32 v133, v133, 31, v236
	v_lshl_add_u32 v133, v133, 2, s5
	ds_read_b32 v133, v133 offset:35716
	s_waitcnt lgkmcnt(4)
; DI void nsacmp_item(const Params& p, int L, int item, char* smem) {
;     ...
;   const int ncv = spos >= 31 ? (spos - 31) / 16 + 1 : 0;
;   const float* lutl = lut + h * 132;
;   float mx = -INFINITY;
; #pragma unroll
;   for (int ct = 0; ct < 4; ++ct)
; #pragma unroll
;     for (int i = 0; i < 16; ++i) {
;       const int c = 32 * ct + (i & 3) + 8 * (i >> 2) + 4 * hh;
;       int dd = spos - 16 * c - 31; dd = dd < 0 ? 0 : (dd > 128 ? 128 : dd);
;       const float sv = (c < ncv) ? (sc[ct][i] + lutl[dd]) : -INFINITY;
;       sc[ct][i] = sv; mx = fmaxf(mx, sv);
;     }
	v_or_b32_e32 v134, 48, v64
	v_lshlrev_b32_e32 v134, 4, v134
	v_sub_u32_e32 v134, v81, v134
	v_med3_i32 v134, v134, 31, v236
	v_lshl_add_u32 v134, v134, 2, s5
	ds_read_b32 v134, v134 offset:35716
	v_or_b32_e32 v135, 49, v64
	v_lshlrev_b32_e32 v135, 4, v135
	v_sub_u32_e32 v135, v81, v135
	v_med3_i32 v135, v135, 31, v236
	v_lshl_add_u32 v135, v135, 2, s5
	ds_read_b32 v135, v135 offset:35716
	v_or_b32_e32 v136, 50, v64
	v_lshlrev_b32_e32 v136, 4, v136
	v_sub_u32_e32 v136, v81, v136
	v_med3_i32 v136, v136, 31, v236
	v_lshl_add_u32 v136, v136, 2, s5
	ds_read_b32 v136, v136 offset:35716
	v_or_b32_e32 v137, 51, v64
	v_lshlrev_b32_e32 v137, 4, v137
	v_sub_u32_e32 v137, v81, v137
	v_med3_i32 v137, v137, 31, v236
	v_lshl_add_u32 v137, v137, 2, s5
	ds_read_b32 v137, v137 offset:35716
	v_or_b32_e32 v138, 56, v64
	v_lshlrev_b32_e32 v138, 4, v138
	v_sub_u32_e32 v138, v81, v138
	v_med3_i32 v138, v138, 31, v236
	v_lshl_add_u32 v138, v138, 2, s5
	ds_read_b32 v138, v138 offset:35716
	v_or_b32_e32 v139, 57, v64
	v_lshlrev_b32_e32 v139, 4, v139
	v_sub_u32_e32 v139, v81, v139
	v_med3_i32 v139, v139, 31, v236
	v_lshl_add_u32 v139, v139, 2, s5
	ds_read_b32 v139, v139 offset:35716
	v_or_b32_e32 v140, 58, v64
	v_lshlrev_b32_e32 v140, 4, v140
	v_sub_u32_e32 v140, v81, v140
	v_med3_i32 v140, v140, 31, v236
	v_lshl_add_u32 v140, v140, 2, s5
	ds_read_b32 v140, v140 offset:35716
	v_or_b32_e32 v141, 59, v64
	v_lshlrev_b32_e32 v141, 4, v141
	v_sub_u32_e32 v141, v81, v141
	v_med3_i32 v141, v141, 31, v236
	v_lshl_add_u32 v141, v141, 2, s5
	ds_read_b32 v141, v141 offset:35716
	s_waitcnt lgkmcnt(4)
	v_or_b32_e32 v142, 64, v64
	v_lshlrev_b32_e32 v142, 4, v142
	v_sub_u32_e32 v142, v81, v142
	v_med3_i32 v142, v142, 31, v236
	v_lshl_add_u32 v142, v142, 2, s5
	ds_read_b32 v142, v142 offset:35716
	v_or_b32_e32 v143, 0x41, v64
	v_lshlrev_b32_e32 v143, 4, v143
	v_sub_u32_e32 v143, v81, v143
	v_med3_i32 v143, v143, 31, v236
	v_lshl_add_u32 v143, v143, 2, s5
	ds_read_b32 v143, v143 offset:35716
	v_or_b32_e32 v144, 0x42, v64
	v_lshlrev_b32_e32 v144, 4, v144
	v_sub_u32_e32 v144, v81, v144
	v_med3_i32 v144, v144, 31, v236
	v_lshl_add_u32 v144, v144, 2, s5
	ds_read_b32 v144, v144 offset:35716
	v_or_b32_e32 v145, 0x43, v64
	v_lshlrev_b32_e32 v145, 4, v145
	v_sub_u32_e32 v145, v81, v145
	v_med3_i32 v145, v145, 31, v236
	v_lshl_add_u32 v145, v145, 2, s5
	ds_read_b32 v145, v145 offset:35716
	v_or_b32_e32 v146, 0x48, v64
	v_lshlrev_b32_e32 v146, 4, v146
	v_sub_u32_e32 v146, v81, v146
	v_med3_i32 v146, v146, 31, v236
	v_lshl_add_u32 v146, v146, 2, s5
	ds_read_b32 v146, v146 offset:35716
	v_or_b32_e32 v147, 0x49, v64
	v_lshlrev_b32_e32 v147, 4, v147
	v_sub_u32_e32 v147, v81, v147
	v_med3_i32 v147, v147, 31, v236
	v_lshl_add_u32 v147, v147, 2, s5
	ds_read_b32 v147, v147 offset:35716
	v_or_b32_e32 v148, 0x4a, v64
	v_lshlrev_b32_e32 v148, 4, v148
	v_sub_u32_e32 v148, v81, v148
	v_med3_i32 v148, v148, 31, v236
	v_lshl_add_u32 v148, v148, 2, s5
	ds_read_b32 v148, v148 offset:35716
	v_or_b32_e32 v149, 0x4b, v64
	v_lshlrev_b32_e32 v149, 4, v149
	v_sub_u32_e32 v149, v81, v149
	v_med3_i32 v149, v149, 31, v236
	v_lshl_add_u32 v149, v149, 2, s5
	ds_read_b32 v149, v149 offset:35716
	s_waitcnt lgkmcnt(4)
	v_or_b32_e32 v150, 0x50, v64
	v_lshlrev_b32_e32 v150, 4, v150
	v_sub_u32_e32 v150, v81, v150
	v_med3_i32 v150, v150, 31, v236
	v_lshl_add_u32 v150, v150, 2, s5
	ds_read_b32 v150, v150 offset:35716
	v_or_b32_e32 v151, 0x51, v64
	v_lshlrev_b32_e32 v151, 4, v151
	v_sub_u32_e32 v151, v81, v151
	v_med3_i32 v151, v151, 31, v236
	v_lshl_add_u32 v151, v151, 2, s5
	ds_read_b32 v151, v151 offset:35716
	v_or_b32_e32 v152, 0x52, v64
	v_lshlrev_b32_e32 v152, 4, v152
	v_sub_u32_e32 v152, v81, v152
	v_med3_i32 v152, v152, 31, v236
	v_lshl_add_u32 v152, v152, 2, s5
	ds_read_b32 v152, v152 offset:35716
	v_or_b32_e32 v153, 0x53, v64
	v_lshlrev_b32_e32 v153, 4, v153
	v_sub_u32_e32 v153, v81, v153
	v_med3_i32 v153, v153, 31, v236
	v_lshl_add_u32 v153, v153, 2, s5
	ds_read_b32 v153, v153 offset:35716
	v_or_b32_e32 v154, 0x58, v64
	v_lshlrev_b32_e32 v154, 4, v154
	v_sub_u32_e32 v154, v81, v154
	v_med3_i32 v154, v154, 31, v236
	v_lshl_add_u32 v154, v154, 2, s5
	ds_read_b32 v154, v154 offset:35716
	v_or_b32_e32 v155, 0x59, v64
	v_lshlrev_b32_e32 v155, 4, v155
	v_sub_u32_e32 v155, v81, v155
	v_med3_i32 v155, v155, 31, v236
	v_lshl_add_u32 v155, v155, 2, s5
	ds_read_b32 v155, v155 offset:35716
	v_or_b32_e32 v156, 0x5a, v64
	v_lshlrev_b32_e32 v156, 4, v156
	v_sub_u32_e32 v156, v81, v156
	v_med3_i32 v156, v156, 31, v236
	v_lshl_add_u32 v156, v156, 2, s5
	ds_read_b32 v156, v156 offset:35716
	v_or_b32_e32 v157, 0x5b, v64
	v_lshlrev_b32_e32 v157, 4, v157
	v_sub_u32_e32 v157, v81, v157
	v_med3_i32 v157, v157, 31, v236
	v_lshl_add_u32 v157, v157, 2, s5
	ds_read_b32 v157, v157 offset:35716
	s_waitcnt lgkmcnt(4)
	v_or_b32_e32 v158, 0x60, v64
	v_lshlrev_b32_e32 v158, 4, v158
	v_sub_u32_e32 v158, v81, v158
	v_med3_i32 v158, v158, 31, v236
	v_lshl_add_u32 v158, v158, 2, s5
	ds_read_b32 v158, v158 offset:35716
	v_or_b32_e32 v159, 0x61, v64
	v_lshlrev_b32_e32 v159, 4, v159
	v_sub_u32_e32 v159, v81, v159
	v_med3_i32 v159, v159, 31, v236
	v_lshl_add_u32 v159, v159, 2, s5
	ds_read_b32 v159, v159 offset:35716
	v_or_b32_e32 v160, 0x62, v64
	v_lshlrev_b32_e32 v160, 4, v160
	v_sub_u32_e32 v160, v81, v160
	v_med3_i32 v160, v160, 31, v236
	v_lshl_add_u32 v160, v160, 2, s5
	ds_read_b32 v160, v160 offset:35716
	v_or_b32_e32 v161, 0x63, v64
	v_lshlrev_b32_e32 v161, 4, v161
	v_sub_u32_e32 v161, v81, v161
	v_med3_i32 v161, v161, 31, v236
	v_lshl_add_u32 v161, v161, 2, s5
	ds_read_b32 v161, v161 offset:35716
	v_or_b32_e32 v162, 0x68, v64
	v_lshlrev_b32_e32 v162, 4, v162
	v_sub_u32_e32 v162, v81, v162
	v_med3_i32 v162, v162, 31, v236
	v_lshl_add_u32 v162, v162, 2, s5
	ds_read_b32 v162, v162 offset:35716
	v_or_b32_e32 v163, 0x69, v64
	v_lshlrev_b32_e32 v163, 4, v163
	v_sub_u32_e32 v163, v81, v163
	v_med3_i32 v163, v163, 31, v236
	v_lshl_add_u32 v163, v163, 2, s5
	ds_read_b32 v163, v163 offset:35716
	v_or_b32_e32 v164, 0x6a, v64
	v_lshlrev_b32_e32 v164, 4, v164
	v_sub_u32_e32 v164, v81, v164
	v_med3_i32 v164, v164, 31, v236
	v_lshl_add_u32 v164, v164, 2, s5
	ds_read_b32 v164, v164 offset:35716
	v_or_b32_e32 v165, 0x6b, v64
	v_lshlrev_b32_e32 v165, 4, v165
	v_sub_u32_e32 v165, v81, v165
	v_med3_i32 v165, v165, 31, v236
	v_lshl_add_u32 v165, v165, 2, s5
	ds_read_b32 v165, v165 offset:35716
	s_waitcnt lgkmcnt(4)
; DI void nsacmp_item(const Params& p, int L, int item, char* smem) {
;     ...
;   const int ncv = spos >= 31 ? (spos - 31) / 16 + 1 : 0;
;   const float* lutl = lut + h * 132;
;   float mx = -INFINITY;
; #pragma unroll
;   for (int ct = 0; ct < 4; ++ct)
; #pragma unroll
;     for (int i = 0; i < 16; ++i) {
;       const int c = 32 * ct + (i & 3) + 8 * (i >> 2) + 4 * hh;
;       int dd = spos - 16 * c - 31; dd = dd < 0 ? 0 : (dd > 128 ? 128 : dd);
;       const float sv = (c < ncv) ? (sc[ct][i] + lutl[dd]) : -INFINITY;
;       sc[ct][i] = sv; mx = fmaxf(mx, sv);
;     }
	v_or_b32_e32 v166, 0x70, v64
	v_lshlrev_b32_e32 v166, 4, v166
	v_sub_u32_e32 v166, v81, v166
	v_med3_i32 v166, v166, 31, v236
	v_lshl_add_u32 v166, v166, 2, s5
	ds_read_b32 v166, v166 offset:35716
	v_or_b32_e32 v167, 0x71, v64
	v_lshlrev_b32_e32 v167, 4, v167
	v_sub_u32_e32 v167, v81, v167
	v_med3_i32 v167, v167, 31, v236
	v_lshl_add_u32 v167, v167, 2, s5
	ds_read_b32 v167, v167 offset:35716
	v_or_b32_e32 v168, 0x72, v64
	v_lshlrev_b32_e32 v168, 4, v168
	v_sub_u32_e32 v168, v81, v168
	v_med3_i32 v168, v168, 31, v236
	v_lshl_add_u32 v168, v168, 2, s5
	ds_read_b32 v168, v168 offset:35716
	v_or_b32_e32 v169, 0x73, v64
	v_lshlrev_b32_e32 v169, 4, v169
	v_sub_u32_e32 v169, v81, v169
	v_med3_i32 v169, v169, 31, v236
	v_lshl_add_u32 v169, v169, 2, s5
	ds_read_b32 v169, v169 offset:35716
	v_or_b32_e32 v170, 0x78, v64
	v_lshlrev_b32_e32 v170, 4, v170
	v_sub_u32_e32 v170, v81, v170
	v_med3_i32 v170, v170, 31, v236
	v_lshl_add_u32 v170, v170, 2, s5
	ds_read_b32 v170, v170 offset:35716
	v_or_b32_e32 v171, 0x79, v64
	v_lshlrev_b32_e32 v171, 4, v171
	v_sub_u32_e32 v171, v81, v171
	v_med3_i32 v171, v171, 31, v236
	v_lshl_add_u32 v171, v171, 2, s5
	ds_read_b32 v171, v171 offset:35716
	v_or_b32_e32 v172, 0x7a, v64
	v_lshlrev_b32_e32 v172, 4, v172
	v_sub_u32_e32 v172, v81, v172
	v_med3_i32 v172, v172, 31, v236
	v_lshl_add_u32 v172, v172, 2, s5
	ds_read_b32 v172, v172 offset:35716
	v_or_b32_e32 v173, 0x7b, v64
	v_lshlrev_b32_e32 v173, 4, v173
	v_sub_u32_e32 v173, v81, v173
	v_med3_i32 v173, v173, 31, v236
	v_lshl_add_u32 v173, v173, 2, s5
	ds_read_b32 v173, v173 offset:35716
	s_waitcnt lgkmcnt(0)
	s_and_saveexec_b64 s[2:3], s[16:17]
	s_cbranch_execz .LBB0_236
	v_med3_i32 v66, v68, 31, v236
	v_lshl_add_u32 v66, v66, 2, s5
	v_mov_b32_e32 v66, v110
	s_waitcnt lgkmcnt(0)
	v_add_f32_e32 v66, v48, v66
.LBB0_236:
	s_or_b64 exec, exec, s[2:3]
	v_cmp_gt_u32_e64 s[2:3], v67, v64
	s_and_b64 s[16:17], vcc, s[2:3]
	s_and_saveexec_b64 s[2:3], s[16:17]
	s_cbranch_execz .LBB0_238
	v_add_u32_e32 v48, -16, v68
	v_med3_i32 v48, v48, 31, v236
	v_lshl_add_u32 v48, v48, 2, s5
	v_mov_b32_e32 v48, v111
	s_waitcnt lgkmcnt(0)
	v_add_f32_e32 v65, v49, v48
.LBB0_238:
	s_or_b64 exec, exec, s[2:3]
	v_or_b32_e32 v68, 2, v64
	v_cmp_ge_u32_e64 s[2:3], v67, v68
	s_and_b64 s[16:17], vcc, s[2:3]
	v_mov_b32_e32 v48, 0xff800000
	v_mov_b32_e32 v49, 0xff800000
	s_and_saveexec_b64 s[2:3], s[16:17]
	s_cbranch_execz .LBB0_240
	v_lshlrev_b32_e32 v49, 4, v68
	v_sub_u32_e32 v49, v81, v49
	v_med3_i32 v49, v49, 31, v236
	v_lshl_add_u32 v49, v49, 2, s5
	v_mov_b32_e32 v49, v112
	s_waitcnt lgkmcnt(0)
	v_add_f32_e32 v49, v50, v49
.LBB0_240:
	s_or_b64 exec, exec, s[2:3]
	v_or_b32_e32 v50, 3, v64
	v_cmp_ge_u32_e64 s[2:3], v67, v50
	s_and_b64 s[16:17], vcc, s[2:3]
	s_and_saveexec_b64 s[2:3], s[16:17]
	s_cbranch_execz .LBB0_242
	v_lshlrev_b32_e32 v48, 4, v50
	v_sub_u32_e32 v48, v81, v48
	v_med3_i32 v48, v48, 31, v236
	v_lshl_add_u32 v48, v48, 2, s5
	v_mov_b32_e32 v48, v113
	s_waitcnt lgkmcnt(0)
	v_add_f32_e32 v48, v51, v48
.LBB0_242:
	s_or_b64 exec, exec, s[2:3]
	v_or_b32_e32 v68, 8, v64
	v_cmp_ge_u32_e64 s[2:3], v67, v68
	s_and_b64 s[16:17], vcc, s[2:3]
	v_mov_b32_e32 v50, 0xff800000
	v_mov_b32_e32 v51, 0xff800000
	s_and_saveexec_b64 s[2:3], s[16:17]
	s_cbranch_execz .LBB0_244
	v_lshlrev_b32_e32 v51, 4, v68
	v_sub_u32_e32 v51, v81, v51
	v_med3_i32 v51, v51, 31, v236
	v_lshl_add_u32 v51, v51, 2, s5
	v_mov_b32_e32 v51, v114
	s_waitcnt lgkmcnt(0)
	v_add_f32_e32 v51, v52, v51
.LBB0_244:
	s_or_b64 exec, exec, s[2:3]
	v_or_b32_e32 v52, 9, v64
	v_cmp_ge_u32_e64 s[2:3], v67, v52
	s_and_b64 s[16:17], vcc, s[2:3]
	s_and_saveexec_b64 s[2:3], s[16:17]
	s_cbranch_execz .LBB0_246
	v_lshlrev_b32_e32 v50, 4, v52
	v_sub_u32_e32 v50, v81, v50
	v_med3_i32 v50, v50, 31, v236
	v_lshl_add_u32 v50, v50, 2, s5
	v_mov_b32_e32 v50, v115
	s_waitcnt lgkmcnt(0)
	v_add_f32_e32 v50, v53, v50
.LBB0_246:
	s_or_b64 exec, exec, s[2:3]
	v_or_b32_e32 v68, 10, v64
	v_cmp_ge_u32_e64 s[2:3], v67, v68
	s_and_b64 s[16:17], vcc, s[2:3]
	v_mov_b32_e32 v52, 0xff800000
	v_mov_b32_e32 v53, 0xff800000
	s_and_saveexec_b64 s[2:3], s[16:17]
	s_cbranch_execz .LBB0_248
	v_lshlrev_b32_e32 v53, 4, v68
	v_sub_u32_e32 v53, v81, v53
	v_med3_i32 v53, v53, 31, v236
	v_lshl_add_u32 v53, v53, 2, s5
	v_mov_b32_e32 v53, v116
	s_waitcnt lgkmcnt(0)
	v_add_f32_e32 v53, v54, v53
.LBB0_248:
	s_or_b64 exec, exec, s[2:3]
	v_or_b32_e32 v54, 11, v64
	v_cmp_ge_u32_e64 s[2:3], v67, v54
	s_and_b64 s[16:17], vcc, s[2:3]
	s_and_saveexec_b64 s[2:3], s[16:17]
	s_cbranch_execz .LBB0_250
	v_lshlrev_b32_e32 v52, 4, v54
	v_sub_u32_e32 v52, v81, v52
	v_med3_i32 v52, v52, 31, v236
	v_lshl_add_u32 v52, v52, 2, s5
	v_mov_b32_e32 v52, v117
	s_waitcnt lgkmcnt(0)
	v_add_f32_e32 v52, v55, v52
.LBB0_250:
	s_or_b64 exec, exec, s[2:3]
	v_or_b32_e32 v68, 16, v64
	v_cmp_ge_u32_e64 s[2:3], v67, v68
	s_and_b64 s[16:17], vcc, s[2:3]
	v_mov_b32_e32 v54, 0xff800000
	v_mov_b32_e32 v55, 0xff800000
	s_and_saveexec_b64 s[2:3], s[16:17]
	s_cbranch_execz .LBB0_252
	v_lshlrev_b32_e32 v55, 4, v68
	v_sub_u32_e32 v55, v81, v55
	v_med3_i32 v55, v55, 31, v236
	v_lshl_add_u32 v55, v55, 2, s5
	v_mov_b32_e32 v55, v118
	s_waitcnt lgkmcnt(0)
	v_add_f32_e32 v55, v56, v55
.LBB0_252:
	s_or_b64 exec, exec, s[2:3]
	v_or_b32_e32 v56, 17, v64
	v_cmp_ge_u32_e64 s[2:3], v67, v56
	s_and_b64 s[16:17], vcc, s[2:3]
	s_and_saveexec_b64 s[2:3], s[16:17]
	s_cbranch_execz .LBB0_254
	v_lshlrev_b32_e32 v54, 4, v56
	v_sub_u32_e32 v54, v81, v54
	v_med3_i32 v54, v54, 31, v236
	v_lshl_add_u32 v54, v54, 2, s5
	v_mov_b32_e32 v54, v119
	s_waitcnt lgkmcnt(0)
	v_add_f32_e32 v54, v57, v54
; DI void nsacmp_item(const Params& p, int L, int item, char* smem) {
;     ...
;   const int ncv = spos >= 31 ? (spos - 31) / 16 + 1 : 0;
;   const float* lutl = lut + h * 132;
;   float mx = -INFINITY;
; #pragma unroll
;   for (int ct = 0; ct < 4; ++ct)
; #pragma unroll
;     for (int i = 0; i < 16; ++i) {
;       const int c = 32 * ct + (i & 3) + 8 * (i >> 2) + 4 * hh;
;       int dd = spos - 16 * c - 31; dd = dd < 0 ? 0 : (dd > 128 ? 128 : dd);
;       const float sv = (c < ncv) ? (sc[ct][i] + lutl[dd]) : -INFINITY;
;       sc[ct][i] = sv; mx = fmaxf(mx, sv);
;     }
.LBB0_254:
	s_or_b64 exec, exec, s[2:3]
	v_or_b32_e32 v68, 18, v64
	v_cmp_ge_u32_e64 s[2:3], v67, v68
	s_and_b64 s[16:17], vcc, s[2:3]
	v_mov_b32_e32 v56, 0xff800000
	v_mov_b32_e32 v57, 0xff800000
	s_and_saveexec_b64 s[2:3], s[16:17]
	s_cbranch_execz .LBB0_256
	v_lshlrev_b32_e32 v57, 4, v68
	v_sub_u32_e32 v57, v81, v57
	v_med3_i32 v57, v57, 31, v236
	v_lshl_add_u32 v57, v57, 2, s5
	v_mov_b32_e32 v57, v120
	s_waitcnt lgkmcnt(0)
	v_add_f32_e32 v57, v58, v57
.LBB0_256:
	s_or_b64 exec, exec, s[2:3]
	v_or_b32_e32 v58, 19, v64
	v_cmp_ge_u32_e64 s[2:3], v67, v58
	s_and_b64 s[16:17], vcc, s[2:3]
	s_and_saveexec_b64 s[2:3], s[16:17]
	s_cbranch_execz .LBB0_258
	v_lshlrev_b32_e32 v56, 4, v58
	v_sub_u32_e32 v56, v81, v56
	v_med3_i32 v56, v56, 31, v236
	v_lshl_add_u32 v56, v56, 2, s5
	v_mov_b32_e32 v56, v121
	s_waitcnt lgkmcnt(0)
	v_add_f32_e32 v56, v59, v56
.LBB0_258:
	s_or_b64 exec, exec, s[2:3]
	v_or_b32_e32 v68, 24, v64
	v_cmp_ge_u32_e64 s[2:3], v67, v68
	s_and_b64 s[16:17], vcc, s[2:3]
	v_mov_b32_e32 v58, 0xff800000
	v_mov_b32_e32 v59, 0xff800000
	s_and_saveexec_b64 s[2:3], s[16:17]
	s_cbranch_execz .LBB0_260
	v_lshlrev_b32_e32 v59, 4, v68
	v_sub_u32_e32 v59, v81, v59
	v_med3_i32 v59, v59, 31, v236
	v_lshl_add_u32 v59, v59, 2, s5
	v_mov_b32_e32 v59, v122
	s_waitcnt lgkmcnt(0)
	v_add_f32_e32 v59, v60, v59
.LBB0_260:
	s_or_b64 exec, exec, s[2:3]
	v_or_b32_e32 v60, 25, v64
	v_cmp_ge_u32_e64 s[2:3], v67, v60
	s_and_b64 s[16:17], vcc, s[2:3]
	s_and_saveexec_b64 s[2:3], s[16:17]
	s_cbranch_execz .LBB0_262
	v_lshlrev_b32_e32 v58, 4, v60
	v_sub_u32_e32 v58, v81, v58
	v_med3_i32 v58, v58, 31, v236
	v_lshl_add_u32 v58, v58, 2, s5
	v_mov_b32_e32 v58, v123
	s_waitcnt lgkmcnt(0)
	v_add_f32_e32 v58, v61, v58
.LBB0_262:
	s_or_b64 exec, exec, s[2:3]
	v_or_b32_e32 v68, 26, v64
	v_cmp_ge_u32_e64 s[2:3], v67, v68
	s_and_b64 s[16:17], vcc, s[2:3]
	v_mov_b32_e32 v60, 0xff800000
	v_mov_b32_e32 v61, 0xff800000
	s_and_saveexec_b64 s[2:3], s[16:17]
	s_cbranch_execz .LBB0_264
	v_lshlrev_b32_e32 v61, 4, v68
	v_sub_u32_e32 v61, v81, v61
	v_med3_i32 v61, v61, 31, v236
	v_lshl_add_u32 v61, v61, 2, s5
	v_mov_b32_e32 v61, v124
	s_waitcnt lgkmcnt(0)
	v_add_f32_e32 v61, v62, v61
.LBB0_264:
	s_or_b64 exec, exec, s[2:3]
	v_or_b32_e32 v62, 27, v64
	v_cmp_ge_u32_e64 s[2:3], v67, v62
	s_and_b64 s[16:17], vcc, s[2:3]
	s_and_saveexec_b64 s[2:3], s[16:17]
	s_cbranch_execz .LBB0_266
	v_lshlrev_b32_e32 v60, 4, v62
	v_sub_u32_e32 v60, v81, v60
	v_med3_i32 v60, v60, 31, v236
	v_lshl_add_u32 v60, v60, 2, s5
	v_mov_b32_e32 v60, v125
	s_waitcnt lgkmcnt(0)
	v_add_f32_e32 v60, v63, v60
.LBB0_266:
	s_or_b64 exec, exec, s[2:3]
	v_or_b32_e32 v68, 32, v64
	v_cmp_ge_u32_e64 s[2:3], v67, v68
	s_and_b64 s[16:17], vcc, s[2:3]
	v_mov_b32_e32 v62, 0xff800000
	v_mov_b32_e32 v63, 0xff800000
	s_and_saveexec_b64 s[2:3], s[16:17]
	s_cbranch_execz .LBB0_268
	v_lshlrev_b32_e32 v63, 4, v68
	v_sub_u32_e32 v63, v81, v63
	v_med3_i32 v63, v63, 31, v236
	v_lshl_add_u32 v63, v63, 2, s5
	v_mov_b32_e32 v63, v126
	s_waitcnt lgkmcnt(0)
	v_add_f32_e32 v63, v32, v63
.LBB0_268:
	s_or_b64 exec, exec, s[2:3]
	v_or_b32_e32 v32, 33, v64
	v_cmp_ge_u32_e64 s[2:3], v67, v32
	s_and_b64 s[16:17], vcc, s[2:3]
	s_and_saveexec_b64 s[2:3], s[16:17]
	s_cbranch_execz .LBB0_270
	v_lshlrev_b32_e32 v32, 4, v32
	v_sub_u32_e32 v32, v81, v32
	v_med3_i32 v32, v32, 31, v236
	v_lshl_add_u32 v32, v32, 2, s5
	v_mov_b32_e32 v32, v127
	s_waitcnt lgkmcnt(0)
	v_add_f32_e32 v62, v33, v32
.LBB0_270:
	s_or_b64 exec, exec, s[2:3]
	v_or_b32_e32 v68, 34, v64
	v_cmp_ge_u32_e64 s[2:3], v67, v68
	s_and_b64 s[16:17], vcc, s[2:3]
	v_mov_b32_e32 v32, 0xff800000
	v_mov_b32_e32 v33, 0xff800000
	s_and_saveexec_b64 s[2:3], s[16:17]
	s_cbranch_execz .LBB0_272
	v_lshlrev_b32_e32 v33, 4, v68
	v_sub_u32_e32 v33, v81, v33
	v_med3_i32 v33, v33, 31, v236
	v_lshl_add_u32 v33, v33, 2, s5
	v_mov_b32_e32 v33, v128
	s_waitcnt lgkmcnt(0)
	v_add_f32_e32 v33, v34, v33
.LBB0_272:
	s_or_b64 exec, exec, s[2:3]
	v_or_b32_e32 v34, 35, v64
	v_cmp_ge_u32_e64 s[2:3], v67, v34
	s_and_b64 s[16:17], vcc, s[2:3]
	s_and_saveexec_b64 s[2:3], s[16:17]
	s_cbranch_execz .LBB0_274
	v_lshlrev_b32_e32 v32, 4, v34
	v_sub_u32_e32 v32, v81, v32
	v_med3_i32 v32, v32, 31, v236
	v_lshl_add_u32 v32, v32, 2, s5
	v_mov_b32_e32 v32, v129
	s_waitcnt lgkmcnt(0)
	v_add_f32_e32 v32, v35, v32
.LBB0_274:
	s_or_b64 exec, exec, s[2:3]
	v_or_b32_e32 v68, 40, v64
	v_cmp_ge_u32_e64 s[2:3], v67, v68
	s_and_b64 s[16:17], vcc, s[2:3]
	v_mov_b32_e32 v34, 0xff800000
	v_mov_b32_e32 v35, 0xff800000
	s_and_saveexec_b64 s[2:3], s[16:17]
	s_cbranch_execz .LBB0_276
	v_lshlrev_b32_e32 v35, 4, v68
	v_sub_u32_e32 v35, v81, v35
	v_med3_i32 v35, v35, 31, v236
	v_lshl_add_u32 v35, v35, 2, s5
	v_mov_b32_e32 v35, v130
	s_waitcnt lgkmcnt(0)
	v_add_f32_e32 v35, v36, v35
.LBB0_276:
	s_or_b64 exec, exec, s[2:3]
	v_or_b32_e32 v36, 41, v64
	v_cmp_ge_u32_e64 s[2:3], v67, v36
	s_and_b64 s[16:17], vcc, s[2:3]
	s_and_saveexec_b64 s[2:3], s[16:17]
	s_cbranch_execz .LBB0_278
	v_lshlrev_b32_e32 v34, 4, v36
	v_sub_u32_e32 v34, v81, v34
	v_med3_i32 v34, v34, 31, v236
	v_lshl_add_u32 v34, v34, 2, s5
	v_mov_b32_e32 v34, v131
	s_waitcnt lgkmcnt(0)
	v_add_f32_e32 v34, v37, v34
.LBB0_278:
	s_or_b64 exec, exec, s[2:3]
	v_or_b32_e32 v68, 42, v64
	v_cmp_ge_u32_e64 s[2:3], v67, v68
	s_and_b64 s[16:17], vcc, s[2:3]
	v_mov_b32_e32 v36, 0xff800000
	v_mov_b32_e32 v37, 0xff800000
	s_and_saveexec_b64 s[2:3], s[16:17]
	s_cbranch_execz .LBB0_280
	v_lshlrev_b32_e32 v37, 4, v68
	v_sub_u32_e32 v37, v81, v37
	v_med3_i32 v37, v37, 31, v236
	v_lshl_add_u32 v37, v37, 2, s5
	v_mov_b32_e32 v37, v132
	s_waitcnt lgkmcnt(0)
	v_add_f32_e32 v37, v38, v37
; DI void nsacmp_item(const Params& p, int L, int item, char* smem) {
;     ...
;   const int ncv = spos >= 31 ? (spos - 31) / 16 + 1 : 0;
;   const float* lutl = lut + h * 132;
;   float mx = -INFINITY;
; #pragma unroll
;   for (int ct = 0; ct < 4; ++ct)
; #pragma unroll
;     for (int i = 0; i < 16; ++i) {
;       const int c = 32 * ct + (i & 3) + 8 * (i >> 2) + 4 * hh;
;       int dd = spos - 16 * c - 31; dd = dd < 0 ? 0 : (dd > 128 ? 128 : dd);
;       const float sv = (c < ncv) ? (sc[ct][i] + lutl[dd]) : -INFINITY;
;       sc[ct][i] = sv; mx = fmaxf(mx, sv);
;     }
.LBB0_280:
	s_or_b64 exec, exec, s[2:3]
	v_or_b32_e32 v38, 43, v64
	v_cmp_ge_u32_e64 s[2:3], v67, v38
	s_and_b64 s[16:17], vcc, s[2:3]
	s_and_saveexec_b64 s[2:3], s[16:17]
	s_cbranch_execz .LBB0_282
	v_lshlrev_b32_e32 v36, 4, v38
	v_sub_u32_e32 v36, v81, v36
	v_med3_i32 v36, v36, 31, v236
	v_lshl_add_u32 v36, v36, 2, s5
	v_mov_b32_e32 v36, v133
	s_waitcnt lgkmcnt(0)
	v_add_f32_e32 v36, v39, v36
.LBB0_282:
	s_or_b64 exec, exec, s[2:3]
	v_or_b32_e32 v68, 48, v64
	v_cmp_ge_u32_e64 s[2:3], v67, v68
	s_and_b64 s[16:17], vcc, s[2:3]
	v_mov_b32_e32 v38, 0xff800000
	v_mov_b32_e32 v39, 0xff800000
	s_and_saveexec_b64 s[2:3], s[16:17]
	s_cbranch_execz .LBB0_284
	v_lshlrev_b32_e32 v39, 4, v68
	v_sub_u32_e32 v39, v81, v39
	v_med3_i32 v39, v39, 31, v236
	v_lshl_add_u32 v39, v39, 2, s5
	v_mov_b32_e32 v39, v134
	s_waitcnt lgkmcnt(0)
	v_add_f32_e32 v39, v40, v39
.LBB0_284:
	s_or_b64 exec, exec, s[2:3]
	v_or_b32_e32 v40, 49, v64
	v_cmp_ge_u32_e64 s[2:3], v67, v40
	s_and_b64 s[16:17], vcc, s[2:3]
	s_and_saveexec_b64 s[2:3], s[16:17]
	s_cbranch_execz .LBB0_286
	v_lshlrev_b32_e32 v38, 4, v40
	v_sub_u32_e32 v38, v81, v38
	v_med3_i32 v38, v38, 31, v236
	v_lshl_add_u32 v38, v38, 2, s5
	v_mov_b32_e32 v38, v135
	s_waitcnt lgkmcnt(0)
	v_add_f32_e32 v38, v41, v38
.LBB0_286:
	s_or_b64 exec, exec, s[2:3]
	v_or_b32_e32 v68, 50, v64
	v_cmp_ge_u32_e64 s[2:3], v67, v68
	s_and_b64 s[16:17], vcc, s[2:3]
	v_mov_b32_e32 v40, 0xff800000
	v_mov_b32_e32 v41, 0xff800000
	s_and_saveexec_b64 s[2:3], s[16:17]
	s_cbranch_execz .LBB0_288
	v_lshlrev_b32_e32 v41, 4, v68
	v_sub_u32_e32 v41, v81, v41
	v_med3_i32 v41, v41, 31, v236
	v_lshl_add_u32 v41, v41, 2, s5
	v_mov_b32_e32 v41, v136
	s_waitcnt lgkmcnt(0)
	v_add_f32_e32 v41, v42, v41
.LBB0_288:
	s_or_b64 exec, exec, s[2:3]
	v_or_b32_e32 v42, 51, v64
	v_cmp_ge_u32_e64 s[2:3], v67, v42
	s_and_b64 s[16:17], vcc, s[2:3]
	s_and_saveexec_b64 s[2:3], s[16:17]
	s_cbranch_execz .LBB0_290
	v_lshlrev_b32_e32 v40, 4, v42
	v_sub_u32_e32 v40, v81, v40
	v_med3_i32 v40, v40, 31, v236
	v_lshl_add_u32 v40, v40, 2, s5
	v_mov_b32_e32 v40, v137
	s_waitcnt lgkmcnt(0)
	v_add_f32_e32 v40, v43, v40
.LBB0_290:
	s_or_b64 exec, exec, s[2:3]
	v_or_b32_e32 v68, 56, v64
	v_cmp_ge_u32_e64 s[2:3], v67, v68
	s_and_b64 s[16:17], vcc, s[2:3]
	v_mov_b32_e32 v42, 0xff800000
	v_mov_b32_e32 v43, 0xff800000
	s_and_saveexec_b64 s[2:3], s[16:17]
	s_cbranch_execz .LBB0_292
	v_lshlrev_b32_e32 v43, 4, v68
	v_sub_u32_e32 v43, v81, v43
	v_med3_i32 v43, v43, 31, v236
	v_lshl_add_u32 v43, v43, 2, s5
	v_mov_b32_e32 v43, v138
	s_waitcnt lgkmcnt(0)
	v_add_f32_e32 v43, v44, v43
.LBB0_292:
	s_or_b64 exec, exec, s[2:3]
	v_or_b32_e32 v44, 57, v64
	v_cmp_ge_u32_e64 s[2:3], v67, v44
	s_and_b64 s[16:17], vcc, s[2:3]
	s_and_saveexec_b64 s[2:3], s[16:17]
	s_cbranch_execz .LBB0_294
	v_lshlrev_b32_e32 v42, 4, v44
	v_sub_u32_e32 v42, v81, v42
	v_med3_i32 v42, v42, 31, v236
	v_lshl_add_u32 v42, v42, 2, s5
	v_mov_b32_e32 v42, v139
	s_waitcnt lgkmcnt(0)
	v_add_f32_e32 v42, v45, v42
.LBB0_294:
	s_or_b64 exec, exec, s[2:3]
	v_or_b32_e32 v68, 58, v64
	v_cmp_ge_u32_e64 s[2:3], v67, v68
	s_and_b64 s[16:17], vcc, s[2:3]
	v_mov_b32_e32 v44, 0xff800000
	v_mov_b32_e32 v45, 0xff800000
	s_and_saveexec_b64 s[2:3], s[16:17]
	s_cbranch_execz .LBB0_296
	v_lshlrev_b32_e32 v45, 4, v68
	v_sub_u32_e32 v45, v81, v45
	v_med3_i32 v45, v45, 31, v236
	v_lshl_add_u32 v45, v45, 2, s5
	v_mov_b32_e32 v45, v140
	s_waitcnt lgkmcnt(0)
	v_add_f32_e32 v45, v46, v45
.LBB0_296:
	s_or_b64 exec, exec, s[2:3]
	v_or_b32_e32 v46, 59, v64
	v_cmp_ge_u32_e64 s[2:3], v67, v46
	s_and_b64 s[16:17], vcc, s[2:3]
	s_and_saveexec_b64 s[2:3], s[16:17]
	s_cbranch_execz .LBB0_298
	v_lshlrev_b32_e32 v44, 4, v46
	v_sub_u32_e32 v44, v81, v44
	v_med3_i32 v44, v44, 31, v236
	v_lshl_add_u32 v44, v44, 2, s5
	v_mov_b32_e32 v44, v141
	s_waitcnt lgkmcnt(0)
	v_add_f32_e32 v44, v47, v44
.LBB0_298:
	s_or_b64 exec, exec, s[2:3]
	v_or_b32_e32 v68, 64, v64
	v_cmp_ge_u32_e64 s[2:3], v67, v68
	s_and_b64 s[16:17], vcc, s[2:3]
	v_mov_b32_e32 v46, 0xff800000
	v_mov_b32_e32 v47, 0xff800000
	s_and_saveexec_b64 s[2:3], s[16:17]
	s_cbranch_execz .LBB0_300
	v_lshlrev_b32_e32 v47, 4, v68
	v_sub_u32_e32 v47, v81, v47
	v_med3_i32 v47, v47, 31, v236
	v_lshl_add_u32 v47, v47, 2, s5
	v_mov_b32_e32 v47, v142
	s_waitcnt lgkmcnt(0)
	v_add_f32_e32 v47, v16, v47
.LBB0_300:
	s_or_b64 exec, exec, s[2:3]
	v_or_b32_e32 v16, 0x41, v64
	v_cmp_ge_u32_e64 s[2:3], v67, v16
	s_and_b64 s[16:17], vcc, s[2:3]
	s_and_saveexec_b64 s[2:3], s[16:17]
	s_cbranch_execz .LBB0_302
	v_lshlrev_b32_e32 v16, 4, v16
	v_sub_u32_e32 v16, v81, v16
	v_med3_i32 v16, v16, 31, v236
	v_lshl_add_u32 v16, v16, 2, s5
	v_mov_b32_e32 v16, v143
	s_waitcnt lgkmcnt(0)
	v_add_f32_e32 v46, v17, v16
.LBB0_302:
	s_or_b64 exec, exec, s[2:3]
	v_or_b32_e32 v16, 0x42, v64
	v_cmp_ge_u32_e64 s[2:3], v67, v16
	s_and_b64 s[16:17], vcc, s[2:3]
	v_mov_b32_e32 v68, 0xff800000
	v_mov_b32_e32 v69, 0xff800000
	s_and_saveexec_b64 s[2:3], s[16:17]
	s_cbranch_execz .LBB0_304
	v_lshlrev_b32_e32 v16, 4, v16
	v_sub_u32_e32 v16, v81, v16
	v_med3_i32 v16, v16, 31, v236
	v_lshl_add_u32 v16, v16, 2, s5
	v_mov_b32_e32 v16, v144
	s_waitcnt lgkmcnt(0)
	v_add_f32_e32 v69, v18, v16
.LBB0_304:
	s_or_b64 exec, exec, s[2:3]
	v_or_b32_e32 v16, 0x43, v64
	v_cmp_ge_u32_e64 s[2:3], v67, v16
	s_and_b64 s[16:17], vcc, s[2:3]
	s_and_saveexec_b64 s[2:3], s[16:17]
	s_cbranch_execz .LBB0_306
	v_lshlrev_b32_e32 v16, 4, v16
	v_sub_u32_e32 v16, v81, v16
	v_med3_i32 v16, v16, 31, v236
	v_lshl_add_u32 v16, v16, 2, s5
	v_mov_b32_e32 v16, v145
	s_waitcnt lgkmcnt(0)
	v_add_f32_e32 v68, v19, v16
; DI void nsacmp_item(const Params& p, int L, int item, char* smem) {
;     ...
;   const int ncv = spos >= 31 ? (spos - 31) / 16 + 1 : 0;
;   const float* lutl = lut + h * 132;
;   float mx = -INFINITY;
; #pragma unroll
;   for (int ct = 0; ct < 4; ++ct)
; #pragma unroll
;     for (int i = 0; i < 16; ++i) {
;       const int c = 32 * ct + (i & 3) + 8 * (i >> 2) + 4 * hh;
;       int dd = spos - 16 * c - 31; dd = dd < 0 ? 0 : (dd > 128 ? 128 : dd);
;       const float sv = (c < ncv) ? (sc[ct][i] + lutl[dd]) : -INFINITY;
;       sc[ct][i] = sv; mx = fmaxf(mx, sv);
;     }
.LBB0_306:
	s_or_b64 exec, exec, s[2:3]
	v_or_b32_e32 v16, 0x48, v64
	v_cmp_ge_u32_e64 s[2:3], v67, v16
	s_and_b64 s[16:17], vcc, s[2:3]
	v_mov_b32_e32 v70, 0xff800000
	v_mov_b32_e32 v71, 0xff800000
	s_and_saveexec_b64 s[2:3], s[16:17]
	s_cbranch_execz .LBB0_308
	v_lshlrev_b32_e32 v16, 4, v16
	v_sub_u32_e32 v16, v81, v16
	v_med3_i32 v16, v16, 31, v236
	v_lshl_add_u32 v16, v16, 2, s5
	v_mov_b32_e32 v16, v146
	s_waitcnt lgkmcnt(0)
	v_add_f32_e32 v71, v20, v16
.LBB0_308:
	s_or_b64 exec, exec, s[2:3]
	v_or_b32_e32 v16, 0x49, v64
	v_cmp_ge_u32_e64 s[2:3], v67, v16
	s_and_b64 s[16:17], vcc, s[2:3]
	s_and_saveexec_b64 s[2:3], s[16:17]
	s_cbranch_execz .LBB0_310
	v_lshlrev_b32_e32 v16, 4, v16
	v_sub_u32_e32 v16, v81, v16
	v_med3_i32 v16, v16, 31, v236
	v_lshl_add_u32 v16, v16, 2, s5
	v_mov_b32_e32 v16, v147
	s_waitcnt lgkmcnt(0)
	v_add_f32_e32 v70, v21, v16
.LBB0_310:
	s_or_b64 exec, exec, s[2:3]
	v_or_b32_e32 v16, 0x4a, v64
	v_cmp_ge_u32_e64 s[2:3], v67, v16
	s_and_b64 s[16:17], vcc, s[2:3]
	v_mov_b32_e32 v72, 0xff800000
	v_mov_b32_e32 v73, 0xff800000
	s_and_saveexec_b64 s[2:3], s[16:17]
	s_cbranch_execz .LBB0_312
	v_lshlrev_b32_e32 v16, 4, v16
	v_sub_u32_e32 v16, v81, v16
	v_med3_i32 v16, v16, 31, v236
	v_lshl_add_u32 v16, v16, 2, s5
	v_mov_b32_e32 v16, v148
	s_waitcnt lgkmcnt(0)
	v_add_f32_e32 v73, v22, v16
.LBB0_312:
	s_or_b64 exec, exec, s[2:3]
	v_or_b32_e32 v16, 0x4b, v64
	v_cmp_ge_u32_e64 s[2:3], v67, v16
	s_and_b64 s[16:17], vcc, s[2:3]
	s_and_saveexec_b64 s[2:3], s[16:17]
	s_cbranch_execz .LBB0_314
	v_lshlrev_b32_e32 v16, 4, v16
	v_sub_u32_e32 v16, v81, v16
	v_med3_i32 v16, v16, 31, v236
	v_lshl_add_u32 v16, v16, 2, s5
	v_mov_b32_e32 v16, v149
	s_waitcnt lgkmcnt(0)
	v_add_f32_e32 v72, v23, v16
.LBB0_314:
	s_or_b64 exec, exec, s[2:3]
	v_or_b32_e32 v16, 0x50, v64
	v_cmp_ge_u32_e64 s[2:3], v67, v16
	s_and_b64 s[16:17], vcc, s[2:3]
	v_mov_b32_e32 v74, 0xff800000
	v_mov_b32_e32 v75, 0xff800000
	s_and_saveexec_b64 s[2:3], s[16:17]
	s_cbranch_execz .LBB0_316
	v_lshlrev_b32_e32 v16, 4, v16
	v_sub_u32_e32 v16, v81, v16
	v_med3_i32 v16, v16, 31, v236
	v_lshl_add_u32 v16, v16, 2, s5
	v_mov_b32_e32 v16, v150
	s_waitcnt lgkmcnt(0)
	v_add_f32_e32 v75, v24, v16
.LBB0_316:
	s_or_b64 exec, exec, s[2:3]
	v_or_b32_e32 v16, 0x51, v64
	v_cmp_ge_u32_e64 s[2:3], v67, v16
	s_and_b64 s[16:17], vcc, s[2:3]
	s_and_saveexec_b64 s[2:3], s[16:17]
	s_cbranch_execz .LBB0_318
	v_lshlrev_b32_e32 v16, 4, v16
	v_sub_u32_e32 v16, v81, v16
	v_med3_i32 v16, v16, 31, v236
	v_lshl_add_u32 v16, v16, 2, s5
	v_mov_b32_e32 v16, v151
	s_waitcnt lgkmcnt(0)
	v_add_f32_e32 v74, v25, v16
.LBB0_318:
	s_or_b64 exec, exec, s[2:3]
	v_or_b32_e32 v16, 0x52, v64
	v_cmp_ge_u32_e64 s[2:3], v67, v16
	s_and_b64 s[16:17], vcc, s[2:3]
	v_mov_b32_e32 v24, 0xff800000
	v_mov_b32_e32 v25, 0xff800000
	s_and_saveexec_b64 s[2:3], s[16:17]
	s_cbranch_execz .LBB0_320
	v_lshlrev_b32_e32 v16, 4, v16
	v_sub_u32_e32 v16, v81, v16
	v_med3_i32 v16, v16, 31, v236
	v_lshl_add_u32 v16, v16, 2, s5
	v_mov_b32_e32 v16, v152
	s_waitcnt lgkmcnt(0)
	v_add_f32_e32 v25, v26, v16
.LBB0_320:
	s_or_b64 exec, exec, s[2:3]
	v_or_b32_e32 v16, 0x53, v64
	v_cmp_ge_u32_e64 s[2:3], v67, v16
	s_and_b64 s[16:17], vcc, s[2:3]
	s_and_saveexec_b64 s[2:3], s[16:17]
	s_cbranch_execz .LBB0_322
	v_lshlrev_b32_e32 v16, 4, v16
	v_sub_u32_e32 v16, v81, v16
	v_med3_i32 v16, v16, 31, v236
	v_lshl_add_u32 v16, v16, 2, s5
	v_mov_b32_e32 v16, v153
	s_waitcnt lgkmcnt(0)
	v_add_f32_e32 v24, v27, v16
.LBB0_322:
	s_or_b64 exec, exec, s[2:3]
	v_or_b32_e32 v16, 0x58, v64
	v_cmp_ge_u32_e64 s[2:3], v67, v16
	s_and_b64 s[16:17], vcc, s[2:3]
	v_mov_b32_e32 v26, 0xff800000
	v_mov_b32_e32 v27, 0xff800000
	s_and_saveexec_b64 s[2:3], s[16:17]
	s_cbranch_execz .LBB0_324
	v_lshlrev_b32_e32 v16, 4, v16
	v_sub_u32_e32 v16, v81, v16
	v_med3_i32 v16, v16, 31, v236
	v_lshl_add_u32 v16, v16, 2, s5
	v_mov_b32_e32 v16, v154
	s_waitcnt lgkmcnt(0)
	v_add_f32_e32 v27, v28, v16
.LBB0_324:
	s_or_b64 exec, exec, s[2:3]
	v_or_b32_e32 v16, 0x59, v64
	v_cmp_ge_u32_e64 s[2:3], v67, v16
	s_and_b64 s[16:17], vcc, s[2:3]
	s_and_saveexec_b64 s[2:3], s[16:17]
	s_cbranch_execz .LBB0_326
	v_lshlrev_b32_e32 v16, 4, v16
	v_sub_u32_e32 v16, v81, v16
	v_med3_i32 v16, v16, 31, v236
	v_lshl_add_u32 v16, v16, 2, s5
	v_mov_b32_e32 v16, v155
	s_waitcnt lgkmcnt(0)
	v_add_f32_e32 v26, v29, v16
.LBB0_326:
	s_or_b64 exec, exec, s[2:3]
	v_or_b32_e32 v16, 0x5a, v64
	v_cmp_ge_u32_e64 s[2:3], v67, v16
	s_and_b64 s[16:17], vcc, s[2:3]
	v_mov_b32_e32 v28, 0xff800000
	v_mov_b32_e32 v29, 0xff800000
	s_and_saveexec_b64 s[2:3], s[16:17]
	s_cbranch_execz .LBB0_328
	v_lshlrev_b32_e32 v16, 4, v16
	v_sub_u32_e32 v16, v81, v16
	v_med3_i32 v16, v16, 31, v236
	v_lshl_add_u32 v16, v16, 2, s5
	v_mov_b32_e32 v16, v156
	s_waitcnt lgkmcnt(0)
	v_add_f32_e32 v29, v30, v16
.LBB0_328:
	s_or_b64 exec, exec, s[2:3]
	v_or_b32_e32 v16, 0x5b, v64
	v_cmp_ge_u32_e64 s[2:3], v67, v16
	s_and_b64 s[16:17], vcc, s[2:3]
	s_and_saveexec_b64 s[2:3], s[16:17]
	s_cbranch_execz .LBB0_330
	v_lshlrev_b32_e32 v16, 4, v16
	v_sub_u32_e32 v16, v81, v16
	v_med3_i32 v16, v16, 31, v236
	v_lshl_add_u32 v16, v16, 2, s5
	v_mov_b32_e32 v16, v157
	s_waitcnt lgkmcnt(0)
	v_add_f32_e32 v28, v31, v16
.LBB0_330:
	s_or_b64 exec, exec, s[2:3]
	v_or_b32_e32 v16, 0x60, v64
	v_cmp_ge_u32_e64 s[2:3], v67, v16
	s_and_b64 s[16:17], vcc, s[2:3]
	v_mov_b32_e32 v30, 0xff800000
	v_mov_b32_e32 v76, 0xff800000
	s_and_saveexec_b64 s[2:3], s[16:17]
	s_cbranch_execz .LBB0_332
	v_lshlrev_b32_e32 v16, 4, v16
	v_sub_u32_e32 v16, v81, v16
	v_med3_i32 v16, v16, 31, v236
	v_lshl_add_u32 v16, v16, 2, s5
	v_mov_b32_e32 v16, v158
	s_waitcnt lgkmcnt(0)
	v_add_f32_e32 v76, v0, v16
; DI void nsacmp_item(const Params& p, int L, int item, char* smem) {
;     ...
;   const int ncv = spos >= 31 ? (spos - 31) / 16 + 1 : 0;
;   const float* lutl = lut + h * 132;
;   float mx = -INFINITY;
; #pragma unroll
;   for (int ct = 0; ct < 4; ++ct)
; #pragma unroll
;     for (int i = 0; i < 16; ++i) {
;       const int c = 32 * ct + (i & 3) + 8 * (i >> 2) + 4 * hh;
;       int dd = spos - 16 * c - 31; dd = dd < 0 ? 0 : (dd > 128 ? 128 : dd);
;       const float sv = (c < ncv) ? (sc[ct][i] + lutl[dd]) : -INFINITY;
;       sc[ct][i] = sv; mx = fmaxf(mx, sv);
;     }
.LBB0_332:
	s_or_b64 exec, exec, s[2:3]
	v_or_b32_e32 v0, 0x61, v64
	v_cmp_ge_u32_e64 s[2:3], v67, v0
	s_and_b64 s[16:17], vcc, s[2:3]
	s_and_saveexec_b64 s[2:3], s[16:17]
	s_cbranch_execz .LBB0_334
	v_lshlrev_b32_e32 v0, 4, v0
	v_sub_u32_e32 v0, v81, v0
	v_med3_i32 v0, v0, 31, v236
	v_lshl_add_u32 v0, v0, 2, s5
	v_mov_b32_e32 v0, v159
	s_waitcnt lgkmcnt(0)
	v_add_f32_e32 v30, v1, v0
.LBB0_334:
	s_or_b64 exec, exec, s[2:3]
	v_or_b32_e32 v0, 0x62, v64
	v_cmp_ge_u32_e64 s[2:3], v67, v0
	s_and_b64 s[16:17], vcc, s[2:3]
	v_mov_b32_e32 v77, 0xff800000
	v_mov_b32_e32 v78, 0xff800000
	s_and_saveexec_b64 s[2:3], s[16:17]
	s_cbranch_execz .LBB0_336
	v_lshlrev_b32_e32 v0, 4, v0
	v_sub_u32_e32 v0, v81, v0
	v_med3_i32 v0, v0, 31, v236
	v_lshl_add_u32 v0, v0, 2, s5
	v_mov_b32_e32 v0, v160
	s_waitcnt lgkmcnt(0)
	v_add_f32_e32 v78, v2, v0
.LBB0_336:
	s_or_b64 exec, exec, s[2:3]
	v_or_b32_e32 v0, 0x63, v64
	v_cmp_ge_u32_e64 s[2:3], v67, v0
	s_and_b64 s[16:17], vcc, s[2:3]
	s_and_saveexec_b64 s[2:3], s[16:17]
	s_cbranch_execz .LBB0_338
	v_lshlrev_b32_e32 v0, 4, v0
	v_sub_u32_e32 v0, v81, v0
	v_med3_i32 v0, v0, 31, v236
	v_lshl_add_u32 v0, v0, 2, s5
	v_mov_b32_e32 v0, v161
	s_waitcnt lgkmcnt(0)
	v_add_f32_e32 v77, v3, v0
.LBB0_338:
	s_or_b64 exec, exec, s[2:3]
	v_or_b32_e32 v0, 0x68, v64
	v_cmp_ge_u32_e64 s[2:3], v67, v0
	s_and_b64 s[16:17], vcc, s[2:3]
	v_mov_b32_e32 v79, 0xff800000
	v_mov_b32_e32 v84, 0xff800000
	s_and_saveexec_b64 s[2:3], s[16:17]
	s_cbranch_execz .LBB0_340
	v_lshlrev_b32_e32 v0, 4, v0
	v_sub_u32_e32 v0, v81, v0
	v_med3_i32 v0, v0, 31, v236
	v_lshl_add_u32 v0, v0, 2, s5
	v_mov_b32_e32 v0, v162
	s_waitcnt lgkmcnt(0)
	v_add_f32_e32 v84, v4, v0
.LBB0_340:
	s_or_b64 exec, exec, s[2:3]
	v_or_b32_e32 v0, 0x69, v64
	v_cmp_ge_u32_e64 s[2:3], v67, v0
	s_and_b64 s[16:17], vcc, s[2:3]
	s_and_saveexec_b64 s[2:3], s[16:17]
	s_cbranch_execz .LBB0_342
	v_lshlrev_b32_e32 v0, 4, v0
	v_sub_u32_e32 v0, v81, v0
	v_med3_i32 v0, v0, 31, v236
	v_lshl_add_u32 v0, v0, 2, s5
	v_mov_b32_e32 v0, v163
	s_waitcnt lgkmcnt(0)
	v_add_f32_e32 v79, v5, v0
.LBB0_342:
	s_or_b64 exec, exec, s[2:3]
	v_or_b32_e32 v0, 0x6a, v64
	v_cmp_ge_u32_e64 s[2:3], v67, v0
	s_and_b64 s[16:17], vcc, s[2:3]
	v_mov_b32_e32 v85, 0xff800000
	v_mov_b32_e32 v86, 0xff800000
	s_and_saveexec_b64 s[2:3], s[16:17]
	s_cbranch_execz .LBB0_344
	v_lshlrev_b32_e32 v0, 4, v0
	v_sub_u32_e32 v0, v81, v0
	v_med3_i32 v0, v0, 31, v236
	v_lshl_add_u32 v0, v0, 2, s5
	v_mov_b32_e32 v0, v164
	s_waitcnt lgkmcnt(0)
	v_add_f32_e32 v86, v6, v0
.LBB0_344:
	s_or_b64 exec, exec, s[2:3]
	v_or_b32_e32 v0, 0x6b, v64
	v_cmp_ge_u32_e64 s[2:3], v67, v0
	s_and_b64 s[16:17], vcc, s[2:3]
	s_and_saveexec_b64 s[2:3], s[16:17]
	s_cbranch_execz .LBB0_346
	v_lshlrev_b32_e32 v0, 4, v0
	v_sub_u32_e32 v0, v81, v0
	v_med3_i32 v0, v0, 31, v236
	v_lshl_add_u32 v0, v0, 2, s5
	v_mov_b32_e32 v0, v165
	s_waitcnt lgkmcnt(0)
	v_add_f32_e32 v85, v7, v0
.LBB0_346:
	s_or_b64 exec, exec, s[2:3]
	v_or_b32_e32 v0, 0x70, v64
	v_cmp_ge_u32_e64 s[2:3], v67, v0
	s_and_b64 s[16:17], vcc, s[2:3]
	v_mov_b32_e32 v87, 0xff800000
	v_mov_b32_e32 v88, 0xff800000
	s_and_saveexec_b64 s[2:3], s[16:17]
	s_cbranch_execz .LBB0_348
	v_lshlrev_b32_e32 v0, 4, v0
	v_sub_u32_e32 v0, v81, v0
	v_med3_i32 v0, v0, 31, v236
	v_lshl_add_u32 v0, v0, 2, s5
	v_mov_b32_e32 v0, v166
	s_waitcnt lgkmcnt(0)
	v_add_f32_e32 v88, v8, v0
.LBB0_348:
	s_or_b64 exec, exec, s[2:3]
	v_or_b32_e32 v0, 0x71, v64
	v_cmp_ge_u32_e64 s[2:3], v67, v0
	s_and_b64 s[16:17], vcc, s[2:3]
	s_and_saveexec_b64 s[2:3], s[16:17]
	s_cbranch_execz .LBB0_350
	v_lshlrev_b32_e32 v0, 4, v0
	v_sub_u32_e32 v0, v81, v0
	v_med3_i32 v0, v0, 31, v236
	v_lshl_add_u32 v0, v0, 2, s5
	v_mov_b32_e32 v0, v167
	s_waitcnt lgkmcnt(0)
	v_add_f32_e32 v87, v9, v0
.LBB0_350:
	s_or_b64 exec, exec, s[2:3]
	v_or_b32_e32 v0, 0x72, v64
	v_cmp_ge_u32_e64 s[2:3], v67, v0
	s_and_b64 s[16:17], vcc, s[2:3]
	v_mov_b32_e32 v89, 0xff800000
	v_mov_b32_e32 v90, 0xff800000
	s_and_saveexec_b64 s[2:3], s[16:17]
	s_cbranch_execz .LBB0_352
	v_lshlrev_b32_e32 v0, 4, v0
	v_sub_u32_e32 v0, v81, v0
	v_med3_i32 v0, v0, 31, v236
	v_lshl_add_u32 v0, v0, 2, s5
	v_mov_b32_e32 v0, v168
	s_waitcnt lgkmcnt(0)
	v_add_f32_e32 v90, v10, v0
.LBB0_352:
	s_or_b64 exec, exec, s[2:3]
	v_or_b32_e32 v0, 0x73, v64
	v_cmp_ge_u32_e64 s[2:3], v67, v0
	s_and_b64 s[16:17], vcc, s[2:3]
	s_and_saveexec_b64 s[2:3], s[16:17]
	s_cbranch_execz .LBB0_354
	v_lshlrev_b32_e32 v0, 4, v0
	v_sub_u32_e32 v0, v81, v0
	v_med3_i32 v0, v0, 31, v236
	v_lshl_add_u32 v0, v0, 2, s5
	v_mov_b32_e32 v0, v169
	s_waitcnt lgkmcnt(0)
	v_add_f32_e32 v89, v11, v0
.LBB0_354:
	s_or_b64 exec, exec, s[2:3]
	v_or_b32_e32 v0, 0x78, v64
	v_cmp_ge_u32_e64 s[2:3], v67, v0
	s_and_b64 s[16:17], vcc, s[2:3]
	v_mov_b32_e32 v91, 0xff800000
	v_mov_b32_e32 v92, 0xff800000
	s_and_saveexec_b64 s[2:3], s[16:17]
	s_cbranch_execz .LBB0_356
	v_lshlrev_b32_e32 v0, 4, v0
	v_sub_u32_e32 v0, v81, v0
	v_med3_i32 v0, v0, 31, v236
	v_lshl_add_u32 v0, v0, 2, s5
	v_mov_b32_e32 v0, v170
	s_waitcnt lgkmcnt(0)
	v_add_f32_e32 v92, v12, v0
.LBB0_356:
	s_or_b64 exec, exec, s[2:3]
	v_or_b32_e32 v0, 0x79, v64
	v_cmp_ge_u32_e64 s[2:3], v67, v0
	s_and_b64 s[16:17], vcc, s[2:3]
	s_and_saveexec_b64 s[2:3], s[16:17]
	s_cbranch_execz .LBB0_358
	v_lshlrev_b32_e32 v0, 4, v0
	v_sub_u32_e32 v0, v81, v0
	v_med3_i32 v0, v0, 31, v236
	v_lshl_add_u32 v0, v0, 2, s5
	v_mov_b32_e32 v0, v171
	s_waitcnt lgkmcnt(0)
	v_add_f32_e32 v91, v13, v0
.LBB0_358:
	s_or_b64 exec, exec, s[2:3]
	v_or_b32_e32 v0, 0x7a, v64
	v_cmp_ge_u32_e64 s[2:3], v67, v0
	s_and_b64 s[16:17], vcc, s[2:3]
	v_mov_b32_e32 v93, 0xff800000
	v_mov_b32_e32 v96, 0xff800000
	s_and_saveexec_b64 s[2:3], s[16:17]
	s_cbranch_execz .LBB0_360
	v_lshlrev_b32_e32 v0, 4, v0
	v_sub_u32_e32 v0, v81, v0
	v_med3_i32 v0, v0, 31, v236
	v_lshl_add_u32 v0, v0, 2, s5
	v_mov_b32_e32 v0, v172
	s_waitcnt lgkmcnt(0)
	v_add_f32_e32 v96, v14, v0
.LBB0_360:
	s_or_b64 exec, exec, s[2:3]
	v_or_b32_e32 v0, 0x7b, v64
	v_cmp_ge_u32_e64 s[2:3], v67, v0
	s_and_b64 s[16:17], vcc, s[2:3]
	s_and_saveexec_b64 s[2:3], s[16:17]
	s_cbranch_execz .LBB0_362
	v_lshlrev_b32_e32 v0, 4, v0
	v_sub_u32_e32 v0, v81, v0
	v_med3_i32 v0, v0, 31, v236
	v_lshl_add_u32 v0, v0, 2, s5
	v_mov_b32_e32 v0, v173
	s_waitcnt lgkmcnt(0)
	v_add_f32_e32 v93, v15, v0
